# P4/P4b phase-order stagger: workgroups with index bit 3 set run the small P4b GEMM before their P4 tiles, so P4 epilogues (memory-bound) overlap the other half's K-loops
# baseline (speedup 1.0000x reference)
_Z8mega_fwd4Args:
	s_load_dwordx8 s[4:11], s[0:1], 0x80
	v_mov_b32_e32 v255, 0
	v_and_b32_e32 v196, 0x3ff, v0
	v_cmp_gt_u32_e32 vcc, 2, v196
	s_waitcnt lgkmcnt(0)
	v_writelane_b32 v251, s4, 0
	s_nop 1
	v_writelane_b32 v251, s5, 1
	v_writelane_b32 v251, s6, 2
	v_writelane_b32 v251, s7, 3
	v_writelane_b32 v251, s8, 4
	v_writelane_b32 v251, s9, 5
	v_writelane_b32 v251, s10, 6
	v_writelane_b32 v251, s11, 7
	s_load_dword s38, s[0:1], 0xb8
	s_load_dwordx4 s[16:19], s[0:1], 0xa0
	s_load_dwordx2 s[10:11], s[0:1], 0xb0
	s_add_u32 s6, s0, 0xb0
	s_addc_u32 s7, s1, 0
	s_and_saveexec_b64 s[8:9], vcc
	v_lshl_add_u32 v1, v196, 2, 0
	v_add_u32_e32 v1, 0x20080, v1
	v_mov_b32_e32 v2, 0
	ds_write_b32 v1, v2
	s_or_b64 exec, exec, s[8:9]
	s_waitcnt lgkmcnt(0)
	s_barrier
	s_getreg_b32 s3, hwreg(HW_REG_XCC_ID, 0, 4)
	s_and_b32 s39, s3, 15
	v_cmp_eq_u32_e64 s[4:5], 0, v196
	s_mov_b64 s[12:13], exec
	s_nop 0
	v_writelane_b32 v251, s4, 8
	s_nop 1
	v_writelane_b32 v251, s5, 9
	s_and_b64 s[4:5], s[12:13], s[4:5]
	s_mov_b64 exec, s[4:5]
	s_cbranch_execz .LBB0_5
	s_mov_b64 s[4:5], exec
	v_mbcnt_lo_u32_b32 v1, s4, 0
	v_mbcnt_hi_u32_b32 v1, s5, v1
	v_cmp_eq_u32_e32 vcc, 0, v1
	s_and_b64 s[8:9], exec, vcc
	s_mov_b64 exec, s[8:9]
	s_cbranch_execz .LBB0_5
	s_lshl_b32 s8, s39, 8
	s_bcnt1_i32_b64 s4, s[4:5]
	v_mov_b32_e32 v1, s8
	v_mov_b32_e32 v2, s4
	global_atomic_add v1, v2, s[18:19] offset:1024

.LBB0_729:
	s_or_b64 exec, exec, s[0:1]
	v_readlane_b32 s0, v254, 34
	v_readlane_b32 s1, v254, 35
	s_lshl_b32 s52, s0, 10
	v_readlane_b32 s0, v253, 3
	v_readlane_b32 s1, v253, 4
	v_mov_b32_e32 v12, v196
	s_waitcnt lgkmcnt(0)
	v_cndmask_b32_e64 v0, 0, 1, s[0:1]
	s_barrier
	s_lshl_b64 s[6:7], s[52:53], 10
	s_mov_b32 s62, 16
	v_readfirstlane_b32 s10, v12
	v_cmp_ne_u32_e64 s[38:39], 1, v0
	s_andn2_b64 vcc, exec, s[0:1]
	s_cbranch_vccnz .LBB0_767
	v_readfirstlane_b32 s32, v255
	s_cmp_lg_u32 s32, 0
	s_cbranch_scc1 .Lp4_go
	s_bitcmp1_b32 s22, 3
	s_cbranch_scc0 .Lp4_go
	v_mov_b32_e32 v255, 1
	s_branch .LBB0_767
.Lp4_go:
	v_lshlrev_b32_e32 v0, 4, v12
	v_add_u32_e32 v2, 0x2000, v0
	v_ashrrev_i32_e32 v3, 31, v2
	v_lshrrev_b32_e32 v3, 22, v3
	v_add_u32_e32 v3, v2, v3
	v_ashrrev_i32_e32 v6, 10, v3
	v_mul_i32_i24_e32 v3, 0x400, v6
	v_sub_u32_e32 v2, v2, v3
	v_lshrrev_b32_e32 v3, 4, v2
	v_bitop3_b32 v2, v3, v2, 32 bitop3:0x6c
	v_ashrrev_i32_e32 v3, 31, v2
	v_lshrrev_b32_e32 v3, 26, v3
	v_add_u32_e32 v3, v2, v3
	v_lshlrev_b32_e32 v4, 3, v6
	s_lshl_b64 s[0:1], s[6:7], 1
	v_readlane_b32 s2, v253, 1
	v_ashrrev_i32_e32 v7, 6, v3
	v_and_b32_e32 v4, -16, v4
	s_add_u32 s63, s2, s0
	v_readlane_b32 s0, v253, 2
	v_add_u32_e32 v4, v7, v4
	s_addc_u32 s64, s0, s1
	v_and_b32_e32 v5, 3, v7
	s_mov_b32 s0, 0x1fffe0
	v_lshrrev_b32_e32 v8, 2, v4
	v_lshlrev_b32_e32 v9, 1, v4
	v_and_b32_e32 v3, 0xc0, v3
	v_and_or_b32 v5, v4, s0, v5
	v_and_b32_e32 v8, 4, v8
	v_and_b32_e32 v9, 24, v9
	v_sub_u32_e32 v2, v2, v3
	v_or3_b32 v5, v5, v8, v9
	v_lshlrev_b32_e32 v8, 5, v6
	v_ashrrev_i16_sdwa v2, v201, sext(v2) dst_sel:DWORD dst_unused:UNUSED_PAD src0_sel:DWORD src1_sel:BYTE_0
	v_and_b32_e32 v9, 32, v8
	v_bfe_i32 v8, v2, 0, 16
	v_add_lshl_u32 v2, v9, v8, 1
	s_waitcnt vmcnt(21)
	v_lshl_add_u32 v162, v5, 11, v2
	s_waitcnt vmcnt(19)
	v_lshl_add_u32 v164, v4, 11, v2
	v_bfe_i32 v2, v12, 27, 1
	v_lshrrev_b32_e32 v2, 22, v2
	v_add_u32_e32 v2, v0, v2
	v_and_b32_e32 v2, 0xfffffc00, v2
	v_sub_u32_e32 v0, v0, v2
	v_lshrrev_b32_e32 v2, 4, v0
	v_ashrrev_i32_e32 v3, 31, v12
	v_bitop3_b32 v0, v2, v0, 32 bitop3:0x6c
	v_lshrrev_b32_e32 v3, 26, v3
	v_ashrrev_i32_e32 v2, 31, v0
	v_add_u32_e32 v3, v12, v3
	v_lshrrev_b32_e32 v2, 26, v2
	v_ashrrev_i32_e32 v10, 6, v3
	v_add_u32_e32 v2, v0, v2
	v_lshlrev_b32_e32 v3, 3, v10
	v_ashrrev_i32_e32 v9, 6, v2
	v_and_b32_e32 v3, -16, v3
	v_add_u32_e32 v3, v9, v3
	v_and_b32_e32 v4, 3, v9
	v_lshrrev_b32_e32 v5, 2, v3
	v_lshlrev_b32_e32 v11, 1, v3
	v_and_b32_e32 v2, 0xc0, v2
	s_ashr_i32 s9, s10, 6
	v_and_or_b32 v4, v3, s0, v4
	v_and_b32_e32 v5, 4, v5
	v_and_b32_e32 v11, 24, v11
	v_sub_u32_e32 v0, v0, v2
	s_ashr_i32 s8, s10, 8
	s_lshl_b32 s65, s9, 10
	v_or3_b32 v4, v4, v5, v11
	v_lshlrev_b32_e32 v5, 5, v10
	v_ashrrev_i16_sdwa v0, v201, sext(v0) dst_sel:DWORD dst_unused:UNUSED_PAD src0_sel:DWORD src1_sel:BYTE_0
	v_readlane_b32 s0, v253, 41
	v_and_b32_e32 v5, 32, v5
	v_bfe_i32 v11, v0, 0, 16
	v_readlane_b32 s1, v253, 42
	s_add_u32 s58, s63, s0
	v_add_lshl_u32 v2, v5, v11, 1
	s_addc_u32 s59, s64, s1
	s_add_i32 s66, s65, 0
	v_lshl_add_u32 v0, v4, 11, v2
	s_add_i32 m0, s66, 0x10000
	s_waitcnt vmcnt(17)
	v_lshl_add_u32 v166, v3, 11, v2
	global_load_lds_dwordx4 v0, s[58:59]
	s_add_i32 m0, s66, 0x12000
	s_add_u32 s0, s58, 0x40000
	global_load_lds_dwordx4 v162, s[58:59]
	s_addc_u32 s1, s59, 0
	s_add_i32 m0, s66, 0x14000
	s_add_i32 s67, s66, 0x2000
	global_load_lds_dwordx4 v0, s[0:1]
	s_add_i32 m0, s66, 0x16000
	s_add_i32 s76, s66, 0x4000
	global_load_lds_dwordx4 v162, s[0:1]
	v_readlane_b32 s0, v253, 45
	s_mov_b32 m0, s66
	v_readlane_b32 s1, v253, 46
	s_add_i32 s77, s66, 0x6000
	v_mov_b32_e32 v163, v1
	s_cmp_eq_u32 s8, 1
	s_mov_b32 s48, s95
	v_lshl_add_u64 v[2:3], s[58:59], 0, v[0:1]
	global_load_lds_dwordx4 v166, s[0:1]
	s_mov_b32 m0, s67
	v_lshl_add_u64 v[4:5], s[58:59], 0, v[162:163]
	global_load_lds_dwordx4 v164, s[0:1]
	v_readlane_b32 s0, v253, 47
	s_mov_b32 m0, s76
	v_readlane_b32 s1, v253, 48
	s_nop 4
	global_load_lds_dwordx4 v166, s[0:1]
	s_mov_b32 m0, s77
	s_nop 0
	global_load_lds_dwordx4 v164, s[0:1]
	s_cselect_b64 s[0:1], -1, 0
	s_cmp_lg_u32 s8, 1
	s_cbranch_scc1 .LBB0_732
	s_barrier

.LBB0_766:
	s_waitcnt vmcnt(0)
	v_readlane_b32 s40, v254, 12
	v_readlane_b32 s58, v251, 28
	v_readlane_b32 s41, v254, 13
	s_mov_b64 s[60:61], 0xfffff
	s_barrier
	v_readfirstlane_b32 s32, v255
	s_cmp_eq_u32 s32, 2
	s_cbranch_scc0 .Lp4_end_ft
	v_mov_b32_e32 v255, 0
	s_branch .LBB0_789
.Lp4_end_ft:
.LBB0_767:
	v_mov_b32_e32 v12, v196
	s_mov_b32 s50, 4
	v_readfirstlane_b32 s2, v12
	s_and_b64 vcc, exec, s[38:39]
	s_cbranch_vccnz .LBB0_789
	v_lshlrev_b32_e32 v0, 4, v12
	v_add_u32_e32 v2, 0x2000, v0
	s_waitcnt lgkmcnt(0)
	v_ashrrev_i32_e32 v3, 31, v2
	v_lshrrev_b32_e32 v3, 22, v3
	v_add_u32_e32 v3, v2, v3
	v_ashrrev_i32_e32 v6, 10, v3
	v_mul_i32_i24_e32 v3, 0x400, v6
	v_sub_u32_e32 v2, v2, v3
	v_lshrrev_b32_e32 v3, 4, v2
	v_bitop3_b32 v2, v3, v2, 32 bitop3:0x6c
	v_ashrrev_i32_e32 v3, 31, v2
	v_lshrrev_b32_e32 v3, 26, v3
	v_add_u32_e32 v3, v2, v3
	v_lshlrev_b32_e32 v4, 3, v6
	s_lshl_b64 s[0:1], s[52:53], 9
	v_readlane_b32 s3, v253, 5
	v_ashrrev_i32_e32 v7, 6, v3
	v_and_b32_e32 v4, -16, v4
	s_add_u32 s51, s3, s0
	v_readlane_b32 s0, v253, 6
	v_add_u32_e32 v4, v7, v4
	s_addc_u32 s52, s0, s1
	v_and_b32_e32 v5, 3, v7
	s_mov_b32 s0, 0x7fffe0
	v_lshrrev_b32_e32 v8, 2, v4
	v_lshlrev_b32_e32 v9, 1, v4
	v_and_b32_e32 v3, 0xc0, v3
	v_and_or_b32 v5, v4, s0, v5
	v_and_b32_e32 v8, 4, v8
	v_and_b32_e32 v9, 24, v9
	v_sub_u32_e32 v2, v2, v3
	v_or3_b32 v5, v5, v8, v9
	v_lshlrev_b32_e32 v8, 5, v6
	v_ashrrev_i16_sdwa v2, v201, sext(v2) dst_sel:DWORD dst_unused:UNUSED_PAD src0_sel:DWORD src1_sel:BYTE_0
	v_and_b32_e32 v9, 32, v8
	v_bfe_i32 v8, v2, 0, 16
	v_add_lshl_u32 v2, v9, v8, 1
	v_lshl_add_u32 v130, v5, 9, v2
	v_lshl_add_u32 v132, v4, 9, v2
	v_bfe_i32 v2, v12, 27, 1
	v_lshrrev_b32_e32 v2, 22, v2
	v_add_u32_e32 v2, v0, v2
	v_and_b32_e32 v2, 0xfffffc00, v2
	v_sub_u32_e32 v0, v0, v2
	v_lshrrev_b32_e32 v2, 4, v0
	v_ashrrev_i32_e32 v3, 31, v12
	v_bitop3_b32 v0, v2, v0, 32 bitop3:0x6c
	v_lshrrev_b32_e32 v3, 26, v3
	v_ashrrev_i32_e32 v2, 31, v0
	v_add_u32_e32 v3, v12, v3
	v_lshrrev_b32_e32 v2, 26, v2
	v_ashrrev_i32_e32 v10, 6, v3
	v_add_u32_e32 v2, v0, v2
	v_lshlrev_b32_e32 v3, 3, v10
	v_ashrrev_i32_e32 v9, 6, v2
	v_and_b32_e32 v3, -16, v3
	v_add_u32_e32 v3, v9, v3
	v_and_b32_e32 v4, 3, v9
	v_lshrrev_b32_e32 v5, 2, v3
	v_lshlrev_b32_e32 v11, 1, v3
	v_and_b32_e32 v2, 0xc0, v2
	s_ashr_i32 s3, s2, 6
	v_and_or_b32 v4, v3, s0, v4
	v_and_b32_e32 v5, 4, v5
	v_and_b32_e32 v11, 24, v11
	v_sub_u32_e32 v0, v0, v2
	s_ashr_i32 s4, s2, 8
	s_lshl_b32 s58, s3, 10
	v_or3_b32 v4, v4, v5, v11
	v_lshlrev_b32_e32 v5, 5, v10
	v_ashrrev_i16_sdwa v0, v201, sext(v0) dst_sel:DWORD dst_unused:UNUSED_PAD src0_sel:DWORD src1_sel:BYTE_0
	v_readlane_b32 s0, v253, 33
	v_and_b32_e32 v5, 32, v5
	v_bfe_i32 v11, v0, 0, 16
	v_readlane_b32 s1, v253, 34
	s_add_u32 s46, s51, s0
	v_add_lshl_u32 v2, v5, v11, 1
	s_addc_u32 s47, s52, s1
	s_add_i32 s59, s58, 0
	v_lshl_add_u32 v0, v4, 9, v2
	s_add_i32 m0, s59, 0x10000
	v_lshl_add_u32 v134, v3, 9, v2
	global_load_lds_dwordx4 v0, s[46:47]
	s_add_i32 m0, s59, 0x12000
	s_add_u32 s0, s46, 0x10000
	global_load_lds_dwordx4 v130, s[46:47]
	s_addc_u32 s1, s47, 0
	s_add_i32 m0, s59, 0x14000
	s_add_i32 s60, s59, 0x2000
	global_load_lds_dwordx4 v0, s[0:1]
	s_add_i32 m0, s59, 0x16000
	s_add_i32 s61, s59, 0x4000
	global_load_lds_dwordx4 v130, s[0:1]
	v_readlane_b32 s0, v253, 35
	s_mov_b32 m0, s59
	v_readlane_b32 s1, v253, 36
	s_add_i32 s62, s59, 0x6000
	v_mov_b32_e32 v131, v1
	s_cmp_eq_u32 s4, 1
	v_lshl_add_u64 v[2:3], s[46:47], 0, v[0:1]
	v_lshl_add_u64 v[4:5], s[46:47], 0, v[130:131]
	global_load_lds_dwordx4 v134, s[0:1]
	s_mov_b32 m0, s60
	s_nop 0
	global_load_lds_dwordx4 v132, s[0:1]
	v_readlane_b32 s0, v253, 37
	s_mov_b32 m0, s61
	v_readlane_b32 s1, v253, 38
	s_nop 4
	global_load_lds_dwordx4 v134, s[0:1]
	s_mov_b32 m0, s62
	s_nop 0
	global_load_lds_dwordx4 v132, s[0:1]
	s_cselect_b64 s[0:1], -1, 0
	s_cmp_lg_u32 s4, 1
	s_cbranch_scc1 .LBB0_770
	s_barrier

.LBB0_788:
	s_waitcnt vmcnt(0)
	v_readlane_b32 s40, v254, 12
	v_readlane_b32 s58, v251, 28
	v_readlane_b32 s41, v254, 13
	s_mov_b64 s[60:61], 0xfffff
	s_barrier
	v_readfirstlane_b32 s32, v255
	s_cmp_eq_u32 s32, 1
	s_cbranch_scc0 .Lp4b_end_ft
	v_mov_b32_e32 v255, 2
	s_branch .LBB0_729
.Lp4b_end_ft:
.LBB0_789:
	s_waitcnt vmcnt(0)
	s_waitcnt vmcnt(0) lgkmcnt(0)
	s_barrier
	s_mov_b64 s[0:1], exec
	v_readlane_b32 s2, v251, 8
	v_readlane_b32 s3, v251, 9
	v_readlane_b32 s46, v251, 53
	v_readlane_b32 s48, v254, 37
	s_and_b64 s[2:3], s[0:1], s[2:3]
	v_readlane_b32 s47, v251, 54
	v_readlane_b32 s49, v254, 38
	s_mov_b64 exec, s[2:3]
	s_cbranch_execz .LBB0_841
	v_readlane_b32 s2, v254, 31
	s_waitcnt vmcnt(0) expcnt(0) lgkmcnt(0)
	s_nop 0
	v_mov_b32_e32 v0, s2
	ds_read_b32 v3, v0
	v_readlane_b32 s2, v254, 32
	s_waitcnt lgkmcnt(0)
	v_cmp_ne_u32_e32 vcc, 0, v3
	v_mov_b32_e32 v0, s2
	ds_read_b32 v2, v0
	s_cbranch_vccnz .LBB0_805
	s_mov_b32 s10, 1
	s_branch .LBB0_793

	.amdhsa_kernel _Z8mega_fwd4Args
		.amdhsa_group_segment_fixed_size 0
		.amdhsa_private_segment_fixed_size 0
		.amdhsa_kernarg_size 432
		.amdhsa_user_sgpr_count 2
		.amdhsa_user_sgpr_dispatch_ptr 0
		.amdhsa_user_sgpr_queue_ptr 0
		.amdhsa_user_sgpr_kernarg_segment_ptr 1
		.amdhsa_user_sgpr_dispatch_id 0
		.amdhsa_user_sgpr_kernarg_preload_length 0
		.amdhsa_user_sgpr_kernarg_preload_offset 0
		.amdhsa_user_sgpr_private_segment_size 0
		.amdhsa_uses_dynamic_stack 0
		.amdhsa_enable_private_segment 0
		.amdhsa_system_sgpr_workgroup_id_x 1
		.amdhsa_system_sgpr_workgroup_id_y 0
		.amdhsa_system_sgpr_workgroup_id_z 0
		.amdhsa_system_sgpr_workgroup_info 0
		.amdhsa_system_vgpr_workitem_id 2
		.amdhsa_next_free_vgpr 256
		.amdhsa_next_free_sgpr 100
		.amdhsa_accum_offset 256
		.amdhsa_reserve_vcc 1
		.amdhsa_float_round_mode_32 0
		.amdhsa_float_round_mode_16_64 0
		.amdhsa_float_denorm_mode_32 3
		.amdhsa_float_denorm_mode_16_64 3
		.amdhsa_dx10_clamp 1
		.amdhsa_ieee_mode 1
		.amdhsa_fp16_overflow 0
		.amdhsa_tg_split 0
		.amdhsa_exception_fp_ieee_invalid_op 0
		.amdhsa_exception_fp_denorm_src 0
		.amdhsa_exception_fp_ieee_div_zero 0
		.amdhsa_exception_fp_ieee_overflow 0
		.amdhsa_exception_fp_ieee_underflow 0
		.amdhsa_exception_fp_ieee_inexact 0
		.amdhsa_exception_int_div_zero 0
	.end_amdhsa_kernel

amdhsa.kernels:
  - .agpr_count:     0
    .args:
      - .offset:         0
        .size:           176
        .value_kind:     by_value
      - .offset:         176
        .size:           4
        .value_kind:     hidden_block_count_x
      - .offset:         180
        .size:           4
        .value_kind:     hidden_block_count_y
      - .offset:         184
        .size:           4
        .value_kind:     hidden_block_count_z
      - .offset:         188
        .size:           2
        .value_kind:     hidden_group_size_x
      - .offset:         190
        .size:           2
        .value_kind:     hidden_group_size_y
      - .offset:         192
        .size:           2
        .value_kind:     hidden_group_size_z
      - .offset:         194
        .size:           2
        .value_kind:     hidden_remainder_x
      - .offset:         196
        .size:           2
        .value_kind:     hidden_remainder_y
      - .offset:         198
        .size:           2
        .value_kind:     hidden_remainder_z
      - .offset:         216
        .size:           8
        .value_kind:     hidden_global_offset_x
      - .offset:         224
        .size:           8
        .value_kind:     hidden_global_offset_y
      - .offset:         232
        .size:           8
        .value_kind:     hidden_global_offset_z
      - .offset:         240
        .size:           2
        .value_kind:     hidden_grid_dims
      - .offset:         264
        .size:           8
        .value_kind:     hidden_multigrid_sync_arg
      - .offset:         296
        .size:           4
        .value_kind:     hidden_dynamic_lds_size
    .group_segment_fixed_size: 0
    .kernarg_segment_align: 8
    .kernarg_segment_size: 432
    .language:       OpenCL C
    .language_version:
      - 2
      - 0
    .max_flat_workgroup_size: 512
    .name:           _Z8mega_fwd4Args
    .private_segment_fixed_size: 0
    .sgpr_count:     106
    .sgpr_spill_count: 272
    .symbol:         _Z8mega_fwd4Args.kd
    .uniform_work_group_size: 1
    .uses_dynamic_stack: false
    .vgpr_count:     256
    .vgpr_spill_count: 0
    .wavefront_size: 64
